# baseline (speedup 1.0000x reference)
; __device__ __forceinline__ unsigned cvt_pk_bf16(float lo, float hi) { unsigned r; asm("v_cvt_pk_bf16_f32 %0, %1, %2" : "=v"(r) : "v"(lo), "v"(hi)); return r; }
; __device__ __forceinline__ void dn_seq_unit(int layer, int sample, int b, int h, unsigned char* shm) {
;     ...
;     bf16_t* W16 = (bf16_t*)shm; bf16_t* QG16 = W16 + 64 * 136; bf16_t* KDT = QG16 + 64 * 136; bf16_t* QK16 = KDT + 128 * 72;
;     bf16_t* ST = QK16 + 64 * 72; bf16_t* VT = ST + 128 * 136; float* Of = (float*)(VT + 128 * 72);
;     const bf16_t* P = (const bf16_t*)(p->ws + WS_P); bf16_t* BR1 = (bf16_t*)(p->ws + WS_BR) + (size_t)MT * 1024;
;     const size_t tokb = sample ? (size_t)MP + (size_t)b * DSEQ : (size_t)b * SEQ;
;     const int rows = sample ? DSEQ : 64, nchunks = sample ? 1 : 32;
;     float* dnn = Of + 64 * 132;
;     if (tid < 128) dnn[tid] = p->in[24][(size_t)layer * 128 + tid];
;     f32x4 aS[8];
; #pragma unroll
;     for (int vt = 0; vt < 8; ++vt) {
;         if (sample) { const float* s = p->in[9] + (((size_t)layer * 16 + b) * 8 + h) * 16384;
; #pragma unroll
;             for (int j = 0; j < 4; ++j) aS[vt][j] = s[(wid * 16 + fq * 4 + j) * 128 + vt * 16 + fr]; }
;         else aS[vt] = (f32x4){0.f, 0.f, 0.f, 0.f};
;     }
; #pragma unroll
;     for (int vt = 0; vt < 8; ++vt) { u32x2 o; o[0] = cvt_pk_bf16(aS[vt][0], aS[vt][1]); o[1] = cvt_pk_bf16(aS[vt][2], aS[vt][3]); *(u32x2*)(ST + (vt * 16 + fr) * 136 + wid * 16 + fq * 4) = o; }
;     u32x4 rw[2], rqg[2], rkd[2], rqk, rz[2]; float ru[4][4]; float regl;
;     const int mi = wid >> 1, tt = tid >> 3, part = tid & 7;
;     rz[0] = (u32x4){0u, 0u, 0u, 0u}; rz[1] = rz[0];
;     ...
;     DN_PREFETCH(0);
;     for (int n = 0; n < nchunks; ++n) {
; #pragma unroll
;         for (int it = 0; it < 2; ++it) { const int idx = (it * 512 + tid) * 8, r = idx >> 7, cc = idx & 127;
;             *(u32x4*)(W16 + r * 136 + cc) = rw[it]; *(u32x4*)(QG16 + r * 136 + cc) = rqg[it];
; #pragma unroll
;             for (int i = 0; i < 8; ++i) KDT[(cc + i) * 72 + r] = (bf16_t)(rkd[it][i >> 1] >> ((i & 1) * 16)); }
;         { const int idx = tid * 8, r = idx >> 6, cc = idx & 63; *(u32x4*)(QK16 + r * 72 + cc) = rqk; }
;         float cu[4][4]; u32x4 cz[2]; const float egl = regl;
.LBB0_769:
	s_or_b64 exec, exec, s[26:27]
	v_and_b32_e32 v1, 56, v66
	v_mul_lo_u32 v2, v70, s89
	v_lshlrev_b32_e32 v1, 1, v1
	v_add3_u32 v1, 0, v2, v1
	v_mul_lo_u32 v2, v99, s96
	v_mul_u32_u24_e32 v3, 0x88, v65
	s_and_b64 s[24:25], s[16:17], exec
	v_add_u32_e32 v2, 0, v2
	v_lshlrev_b32_e32 v3, 1, v3
	v_lshlrev_b32_e32 v131, 1, v130
	v_add3_u32 v160, v2, v3, v131
	v_add3_u32 v136, 0, v3, v131
	v_lshlrev_b32_e32 v3, 5, v99
	v_readlane_b32 s24, v254, 9
	v_readlane_b32 s25, v254, 10
	v_and_b32_e32 v133, 0x78, v66
	v_add3_u32 v137, s24, v3, v130
	v_lshlrev_b32_e32 v3, 11, v99
	v_sub_u32_e32 v2, v2, v3
	v_mul_u32_u24_e32 v3, 0x48, v65
	v_lshlrev_b32_e32 v3, 1, v3
	v_add3_u32 v162, s24, v3, v131
	s_movk_i32 s24, 0x900
	v_add3_u32 v161, v2, v3, v131
	v_mul_lo_u32 v2, v96, s24
	v_add_u32_e32 v2, 0, v2
	s_movk_i32 s24, 0x210
	v_add3_u32 v163, v2, v3, v131
	v_mul_lo_u32 v2, v70, s24
	v_add_u32_e32 v70, s25, v2
	v_lshl_add_u64 v[2:3], v[128:129], 1, s[22:23]
	v_lshl_add_u32 v132, v133, 1, 0
	v_lshlrev_b32_e32 v164, 6, v64
	v_lshl_add_u64 v[2:3], v[126:127], 1, v[2:3]
	s_mov_b64 s[22:23], 0x23060000
	v_ashrrev_i32_e32 v64, 7, v66
	v_lshl_add_u64 v[2:3], v[2:3], 0, s[22:23]
	v_mad_u64_u32 v[130:131], s[22:23], v64, s95, v[132:133]
	v_ashrrev_i32_e32 v68, 7, v68
	v_mul_u32_u24_e32 v66, 0x90, v133
	v_mad_u64_u32 v[132:133], s[22:23], v68, s95, v[132:133]
	v_or_b32_e32 v131, 1, v69
	v_lshl_or_b32 v133, v131, 4, v65
	v_mul_u32_u24_e32 v139, 0x90, v133
	v_or_b32_e32 v133, 2, v69
	v_or_b32_e32 v142, 3, v69
	v_mul_u32_u24_e32 v71, 0x110, v65
	v_lshl_add_u32 v99, v65, 2, s25
	v_lshl_or_b32 v141, v133, 4, v65
	v_lshl_or_b32 v65, v142, 4, v65
	v_lshl_add_u32 v64, v64, 1, 0
	v_lshl_add_u32 v68, v68, 1, 0
	v_mul_u32_u24_e32 v96, 0x1100, v69
	v_mad_u32_u24 v138, v69, s96, s96
	v_mad_u32_u24 v140, v69, s96, v220
	v_mad_u32_u24 v143, v69, s96, v221
	v_mul_u32_u24_e32 v65, 0x90, v65
	v_mul_u32_u24_e32 v144, 0x900, v69
	v_lshl_add_u32 v69, v69, 6, v99
	v_mul_lo_u32 v67, v67, s24
	v_lshl_add_u32 v145, v131, 6, v99
	v_lshl_add_u32 v146, v133, 6, v99
	v_lshl_add_u32 v99, v142, 6, v99
	v_mul_i32_i24_e32 v135, 0x110, v155
	v_mul_u32_u24_e32 v98, 0x90, v98
	v_mul_u32_u24_e32 v141, 0x90, v141
	v_lshlrev_b32_e32 v232, 4, v212
	v_and_b32_e32 v232, 0x70, v232
	v_xor_b32_e32 v64, v64, v232
	v_xor_b32_e32 v68, v68, v232
	v_and_b32_e32 v233, 15, v212
	v_lshrrev_b32_e32 v234, 3, v233
	v_lshrrev_b32_e32 v235, 6, v212
	v_and_b32_e32 v236, 1, v235
	v_lshl_or_b32 v234, v236, 1, v234
	v_bfe_u32 v236, v212, 4, 2
	v_xor_b32_e32 v234, v234, v236
	v_lshlrev_b32_e32 v234, 4, v234
	v_mul_u32_u24_e32 v236, 0x900, v235
	v_mul_u32_u24_e32 v233, 0x90, v233
	v_add3_u32 v234, v234, v236, v233
	v_bfe_u32 v235, v235, 1, 1
	v_lshlrev_b32_e32 v235, 6, v235
	v_add_u32_e32 v252, v234, v235
	v_xor_b32_e32 v235, 64, v235
	v_add_u32_e32 v253, v234, v235
	v_add_u32_e32 v131, v64, v66
	v_add_u32_e32 v133, v68, v66
	v_add_u32_e32 v172, v137, v65
	v_add_u32_e32 v174, v69, v67
	v_add_u32_e32 v175, v145, v67
	v_add_u32_e32 v176, v146, v67
	v_add_u32_e32 v177, v99, v67
	v_add_u32_e32 v178, v134, v71
	v_add_u32_e32 v180, v70, v164
	s_waitcnt vmcnt(1)
	v_mov_b64_e32 v[64:65], v[76:77]
	s_waitcnt vmcnt(0)
	v_mov_b64_e32 v[68:69], v[72:73]
	s_mov_b32 s11, s34
	s_cselect_b32 s26, 32, 1
	s_add_i32 s27, s33, 8
	s_mov_b32 s22, 0
	v_add_u32_e32 v165, v136, v96
	v_add_u32_e32 v166, v137, v98
	v_add_u32_e32 v167, v136, v138
	v_add_u32_e32 v168, v137, v139
	v_add_u32_e32 v169, v136, v140
	v_add_u32_e32 v170, v137, v141
	v_add_u32_e32 v171, v136, v143
	v_add_u32_e32 v173, v162, v144
	v_add_u32_e32 v179, v134, v135
	s_mov_b32 s33, 0
	v_mov_b32_e32 v196, v88
	v_mov_b32_e32 v193, v80
	v_mov_b32_e32 v194, v81
	v_mov_b32_e32 v189, v84
	v_mov_b32_e32 v190, v85
	v_mov_b32_e32 v191, v86
	v_mov_b32_e32 v192, v87
	v_mov_b32_e32 v188, v92
	v_mov_b32_e32 v187, v91
	v_mov_b32_e32 v186, v90
	v_mov_b32_e32 v185, v89
	v_mov_b32_e32 v184, v97
	v_mov_b32_e32 v183, v95
	v_mov_b32_e32 v182, v94
	v_mov_b32_e32 v181, v93
	v_mov_b32_e32 v195, v82
	v_mov_b32_e32 v197, v83
	v_mov_b64_e32 v[66:67], v[78:79]
	v_mov_b64_e32 v[70:71], v[74:75]

; __device__ __forceinline__ unsigned cvt_pk_bf16(float lo, float hi) { unsigned r; asm("v_cvt_pk_bf16_f32 %0, %1, %2" : "=v"(r) : "v"(lo), "v"(hi)); return r; }
; __device__ __forceinline__ void dn_seq_unit(int layer, int sample, int b, int h, unsigned char* shm) {
;     ...
; #pragma unroll
;         for (int q = 0; q < 4; ++q) { const int ni = (wid & 1) * 4 + q;
;             f32x4 a = (f32x4){0.f, 0.f, 0.f, 0.f};
;             a = mma_tile(W16 + mi * 16 * 136, 136, ST + ni * 16 * 136, 136, 128, a, fr, fq);
;             u32x2 o; o[0] = cvt_pk_bf16(cu[q][0] - a[0], cu[q][1] - a[1]); o[1] = cvt_pk_bf16(cu[q][2] - a[2], cu[q][3] - a[3]);
;             *(u32x2*)(VT + (ni * 16 + fr) * 72 + mi * 16 + fq * 4) = o; }
;         __syncthreads();
; #pragma unroll
;         for (int q = 0; q < 4; ++q) { const int ni = (wid & 1) * 4 + q;
;             f32x4 a = (f32x4){0.f, 0.f, 0.f, 0.f};
;             a = mma_tile(QG16 + mi * 16 * 136, 136, ST + ni * 16 * 136, 136, 128, a, fr, fq);
;             a = mma_tile(QK16 + mi * 16 * 72, 72, VT + ni * 16 * 72, 72, 64, a, fr, fq);
; #pragma unroll
;             for (int j = 0; j < 4; ++j) Of[(mi * 16 + fq * 4 + j) * 132 + ni * 16 + fr] = a[j]; }
.LBB0_774:
	ds_read_b128 v[134:137], v160
	ds_read_b128 v[138:141], v160 offset:64
	ds_read_b128 v[142:145], v160 offset:128
	ds_read_b128 v[146:149], v160 offset:192
	ds_read_b128 v[198:201], v165 offset:62464
	ds_read_b128 v[202:205], v165 offset:62528
	ds_read_b128 v[206:209], v165 offset:62592
	ds_read_b128 v[232:235], v165 offset:62656
	ds_read_b128 v[236:239], v167 offset:62464
	ds_read_b128 v[240:243], v167 offset:62528
	ds_read_b128 v[244:247], v167 offset:62592
	ds_read_b128 v[248:251], v167 offset:62656
	s_waitcnt lgkmcnt(11)
	s_waitcnt lgkmcnt(7)
	v_mfma_f32_16x16x32_bf16 v[150:153], v[134:137], v[198:201], 0
	s_waitcnt lgkmcnt(6)
	v_mfma_f32_16x16x32_bf16 v[150:153], v[138:141], v[202:205], v[150:153]
	s_waitcnt lgkmcnt(5)
	v_mfma_f32_16x16x32_bf16 v[150:153], v[142:145], v[206:209], v[150:153]
	s_waitcnt lgkmcnt(4)
	v_mfma_f32_16x16x32_bf16 v[150:153], v[146:149], v[232:235], v[150:153]
	ds_read_b128 v[198:201], v169 offset:62464
	ds_read_b128 v[202:205], v169 offset:62528
	ds_read_b128 v[206:209], v169 offset:62592
	ds_read_b128 v[232:235], v169 offset:62656
	s_waitcnt lgkmcnt(7)
	v_mfma_f32_16x16x32_bf16 v[228:231], v[134:137], v[236:239], 0
	s_waitcnt lgkmcnt(6)
	v_mfma_f32_16x16x32_bf16 v[228:231], v[138:141], v[240:243], v[228:231]
	s_waitcnt lgkmcnt(5)
	v_mfma_f32_16x16x32_bf16 v[228:231], v[142:145], v[244:247], v[228:231]
	s_waitcnt lgkmcnt(4)
	v_mfma_f32_16x16x32_bf16 v[228:231], v[146:149], v[248:251], v[228:231]
	ds_read_b128 v[236:239], v171 offset:62464
	ds_read_b128 v[240:243], v171 offset:62528
	ds_read_b128 v[244:247], v171 offset:62592
	ds_read_b128 v[248:251], v171 offset:62656
	v_pk_mul_f32 v[4:5], v[4:5], v[88:89] op_sel_hi:[1,0]
	v_pk_mul_f32 v[6:7], v[6:7], v[88:89] op_sel_hi:[1,0]
	v_pk_mul_f32 v[8:9], v[8:9], v[88:89] op_sel_hi:[1,0]
	v_pk_mul_f32 v[10:11], v[10:11], v[88:89] op_sel_hi:[1,0]
	v_pk_mul_f32 v[12:13], v[12:13], v[88:89] op_sel_hi:[1,0]
	v_pk_mul_f32 v[14:15], v[14:15], v[88:89] op_sel_hi:[1,0]
	v_pk_mul_f32 v[16:17], v[16:17], v[88:89] op_sel_hi:[1,0]
	v_pk_mul_f32 v[18:19], v[18:19], v[88:89] op_sel_hi:[1,0]
	v_sub_f32_e32 v93, v93, v150
	v_sub_f32_e32 v94, v94, v151
	v_cvt_pk_bf16_f32 v94, v93, v94
	v_sub_f32_e32 v93, v95, v152
	v_sub_f32_e32 v95, v97, v153
	v_cvt_pk_bf16_f32 v95, v93, v95
	ds_write_b64 v166, v[94:95]
	s_waitcnt lgkmcnt(8)
	v_mfma_f32_16x16x32_bf16 v[150:153], v[134:137], v[198:201], 0
	s_waitcnt lgkmcnt(7)
	v_mfma_f32_16x16x32_bf16 v[150:153], v[138:141], v[202:205], v[150:153]
	s_waitcnt lgkmcnt(6)
	v_mfma_f32_16x16x32_bf16 v[150:153], v[142:145], v[206:209], v[150:153]
	s_waitcnt lgkmcnt(5)
	v_mfma_f32_16x16x32_bf16 v[150:153], v[146:149], v[232:235], v[150:153]
	v_pk_mul_f32 v[20:21], v[20:21], v[88:89] op_sel_hi:[1,0]
	v_pk_mul_f32 v[22:23], v[22:23], v[88:89] op_sel_hi:[1,0]
	v_pk_mul_f32 v[24:25], v[24:25], v[88:89] op_sel_hi:[1,0]
	v_pk_mul_f32 v[26:27], v[26:27], v[88:89] op_sel_hi:[1,0]
	v_pk_mul_f32 v[28:29], v[28:29], v[88:89] op_sel_hi:[1,0]
	v_pk_mul_f32 v[30:31], v[30:31], v[88:89] op_sel_hi:[1,0]
	v_pk_mul_f32 v[32:33], v[32:33], v[88:89] op_sel_hi:[1,0]
	v_pk_mul_f32 v[34:35], v[34:35], v[88:89] op_sel_hi:[1,0]
	v_sub_f32_e32 v89, v89, v228
	v_sub_f32_e32 v90, v90, v229
	v_cvt_pk_bf16_f32 v90, v89, v90
	v_sub_f32_e32 v89, v91, v230
	v_sub_f32_e32 v91, v92, v231
	v_cvt_pk_bf16_f32 v91, v89, v91
	ds_write_b64 v168, v[90:91]
	s_waitcnt lgkmcnt(5)
	v_mfma_f32_16x16x32_bf16 v[228:231], v[134:137], v[236:239], 0
	s_waitcnt lgkmcnt(4)
	v_mfma_f32_16x16x32_bf16 v[228:231], v[138:141], v[240:243], v[228:231]
	s_waitcnt lgkmcnt(3)
	v_mfma_f32_16x16x32_bf16 v[228:231], v[142:145], v[244:247], v[228:231]
	s_waitcnt lgkmcnt(2)
	v_mfma_f32_16x16x32_bf16 v[228:231], v[146:149], v[248:251], v[228:231]
	v_sub_f32_e32 v87, v87, v150
	v_sub_f32_e32 v86, v86, v151
	v_cvt_pk_bf16_f32 v86, v87, v86
	v_sub_f32_e32 v85, v85, v152
	v_sub_f32_e32 v84, v84, v153
	v_cvt_pk_bf16_f32 v87, v85, v84
	ds_write_b64 v170, v[86:87]
	s_nop 1
	v_sub_f32_e32 v81, v81, v228
	v_sub_f32_e32 v80, v80, v229
	v_cvt_pk_bf16_f32 v80, v81, v80
	v_sub_f32_e32 v81, v82, v230
	v_sub_f32_e32 v82, v83, v231
	v_cvt_pk_bf16_f32 v81, v81, v82
	ds_write_b64 v172, v[80:81]
	s_waitcnt lgkmcnt(0)
	s_barrier
	ds_read_b128 v[134:137], v160 offset:17408
	ds_read_b128 v[138:141], v160 offset:17472
	ds_read_b128 v[142:145], v160 offset:17536
	ds_read_b128 v[146:149], v160 offset:17600
	ds_read_b128 v[198:201], v165 offset:62464
	ds_read_b128 v[202:205], v165 offset:62528
	ds_read_b128 v[206:209], v165 offset:62592
	ds_read_b128 v[232:235], v165 offset:62656
	ds_read_b128 v[236:239], v167 offset:62464
	ds_read_b128 v[240:243], v167 offset:62528
	ds_read_b128 v[244:247], v167 offset:62592
	ds_read_b128 v[248:251], v167 offset:62656
	ds_read_b128 v[88:91], v161 offset:53248
	ds_read_b128 v[92:95], v161 offset:53312
	s_waitcnt lgkmcnt(13)
	s_waitcnt lgkmcnt(9)
	v_mfma_f32_16x16x32_bf16 v[150:153], v[134:137], v[198:201], 0
	s_waitcnt lgkmcnt(8)
	v_mfma_f32_16x16x32_bf16 v[150:153], v[138:141], v[202:205], v[150:153]
	s_waitcnt lgkmcnt(7)
	v_mfma_f32_16x16x32_bf16 v[150:153], v[142:145], v[206:209], v[150:153]
	s_waitcnt lgkmcnt(6)
	v_mfma_f32_16x16x32_bf16 v[150:153], v[146:149], v[232:235], v[150:153]
	ds_read_b128 v[198:201], v169 offset:62464
	ds_read_b128 v[202:205], v169 offset:62528
	ds_read_b128 v[206:209], v169 offset:62592
	ds_read_b128 v[232:235], v169 offset:62656
	s_waitcnt lgkmcnt(9)
	v_mfma_f32_16x16x32_bf16 v[228:231], v[134:137], v[236:239], 0
	s_waitcnt lgkmcnt(8)
	v_mfma_f32_16x16x32_bf16 v[228:231], v[138:141], v[240:243], v[228:231]
	s_waitcnt lgkmcnt(7)
; __device__ __forceinline__ void dn_seq_unit(int layer, int sample, int b, int h, unsigned char* shm) {
;     ...
; #pragma unroll
;         for (int q = 0; q < 4; ++q) { const int ni = (wid & 1) * 4 + q;
;             f32x4 a = (f32x4){0.f, 0.f, 0.f, 0.f};
;             a = mma_tile(QG16 + mi * 16 * 136, 136, ST + ni * 16 * 136, 136, 128, a, fr, fq);
;             a = mma_tile(QK16 + mi * 16 * 72, 72, VT + ni * 16 * 72, 72, 64, a, fr, fq);
; #pragma unroll
;             for (int j = 0; j < 4; ++j) Of[(mi * 16 + fq * 4 + j) * 132 + ni * 16 + fr] = a[j]; }
; #pragma unroll
;         for (int vt = 0; vt < 8; ++vt) { aS[vt] *= egl; aS[vt] = mma_tile(KDT + wid * 16 * 72, 72, VT + vt * 16 * 72, 72, 64, aS[vt], fr, fq); }
;         __syncthreads();
	v_mfma_f32_16x16x32_bf16 v[228:231], v[142:145], v[244:247], v[228:231]
	s_waitcnt lgkmcnt(6)
	v_mfma_f32_16x16x32_bf16 v[228:231], v[146:149], v[248:251], v[228:231]
	ds_read_b128 v[236:239], v171 offset:62464
	ds_read_b128 v[240:243], v171 offset:62528
	ds_read_b128 v[244:247], v171 offset:62592
	ds_read_b128 v[248:251], v171 offset:62656
	s_waitcnt lgkmcnt(7)
	v_mfma_f32_16x16x32_bf16 v[80:83], v[134:137], v[198:201], 0
	s_waitcnt lgkmcnt(6)
	v_mfma_f32_16x16x32_bf16 v[80:83], v[138:141], v[202:205], v[80:83]
	s_waitcnt lgkmcnt(5)
	v_mfma_f32_16x16x32_bf16 v[80:83], v[142:145], v[206:209], v[80:83]
	s_waitcnt lgkmcnt(4)
	v_mfma_f32_16x16x32_bf16 v[80:83], v[146:149], v[232:235], v[80:83]
	ds_read_b128 v[198:201], v173 offset:0
	ds_read_b128 v[202:205], v173 offset:64
	ds_read_b128 v[206:209], v173 offset:2304
	ds_read_b128 v[232:235], v173 offset:2368
	s_waitcnt lgkmcnt(7)
	v_mfma_f32_16x16x32_bf16 v[84:87], v[134:137], v[236:239], 0
	s_waitcnt lgkmcnt(6)
	v_mfma_f32_16x16x32_bf16 v[84:87], v[138:141], v[240:243], v[84:87]
	s_waitcnt lgkmcnt(5)
	v_mfma_f32_16x16x32_bf16 v[84:87], v[142:145], v[244:247], v[84:87]
	s_waitcnt lgkmcnt(4)
	v_mfma_f32_16x16x32_bf16 v[84:87], v[146:149], v[248:251], v[84:87]
	ds_read_b128 v[236:239], v173 offset:4608
	ds_read_b128 v[240:243], v173 offset:4672
	ds_read_b128 v[244:247], v173 offset:6912
	ds_read_b128 v[248:251], v173 offset:6976
	ds_read_b128 v[134:137], v252 offset:34816
	ds_read_b128 v[138:141], v253 offset:34816
	ds_read_b128 v[142:145], v162 offset:0
	ds_read_b128 v[146:149], v162 offset:64
	s_waitcnt lgkmcnt(11)
	v_mfma_f32_16x16x32_bf16 v[150:153], v[88:91], v[198:201], v[150:153]
	s_waitcnt lgkmcnt(10)
	v_mfma_f32_16x16x32_bf16 v[150:153], v[92:95], v[202:205], v[150:153]
	ds_read_b128 v[198:201], v162 offset:2304
	ds_read_b128 v[202:205], v162 offset:2368
	s_waitcnt lgkmcnt(11)
	v_mfma_f32_16x16x32_bf16 v[228:231], v[88:91], v[206:209], v[228:231]
	s_waitcnt lgkmcnt(10)
	v_mfma_f32_16x16x32_bf16 v[228:231], v[92:95], v[232:235], v[228:231]
	ds_read_b128 v[206:209], v162 offset:4608
	ds_read_b128 v[232:235], v162 offset:4672
	s_waitcnt lgkmcnt(11)
	v_mfma_f32_16x16x32_bf16 v[80:83], v[88:91], v[236:239], v[80:83]
	s_waitcnt lgkmcnt(10)
	v_mfma_f32_16x16x32_bf16 v[80:83], v[92:95], v[240:243], v[80:83]
	ds_read_b128 v[236:239], v162 offset:6912
	ds_read_b128 v[240:243], v162 offset:6976
	s_waitcnt lgkmcnt(11)
	v_mfma_f32_16x16x32_bf16 v[84:87], v[88:91], v[244:247], v[84:87]
	s_waitcnt lgkmcnt(10)
	v_mfma_f32_16x16x32_bf16 v[84:87], v[92:95], v[248:251], v[84:87]
	ds_read_b128 v[244:247], v162 offset:9216
	ds_read_b128 v[248:251], v162 offset:9280
	s_waitcnt lgkmcnt(11)
	s_waitcnt lgkmcnt(9)
	v_mfma_f32_16x16x32_bf16 v[4:7], v[134:137], v[142:145], v[4:7]
	s_waitcnt lgkmcnt(8)
	v_mfma_f32_16x16x32_bf16 v[4:7], v[138:141], v[146:149], v[4:7]
	ds_read_b128 v[142:145], v162 offset:11520
	ds_read_b128 v[146:149], v162 offset:11584
	ds_write2_b32 v174, v150, v151 offset1:132
	v_add_u32_e32 v96, 0x400, v174
	ds_write2_b32 v96, v152, v153 offset0:8 offset1:140
	s_waitcnt lgkmcnt(11)
	v_mfma_f32_16x16x32_bf16 v[8:11], v[134:137], v[198:201], v[8:11]
	s_waitcnt lgkmcnt(10)
	v_mfma_f32_16x16x32_bf16 v[8:11], v[138:141], v[202:205], v[8:11]
	ds_read_b128 v[198:201], v162 offset:13824
	ds_read_b128 v[202:205], v162 offset:13888
	ds_write2_b32 v175, v228, v229 offset1:132
	v_add_u32_e32 v96, 0x400, v175
	ds_write2_b32 v96, v230, v231 offset0:8 offset1:140
	s_waitcnt lgkmcnt(13)
	v_mfma_f32_16x16x32_bf16 v[12:15], v[134:137], v[206:209], v[12:15]
	s_waitcnt lgkmcnt(12)
	v_mfma_f32_16x16x32_bf16 v[12:15], v[138:141], v[232:235], v[12:15]
	ds_read_b128 v[206:209], v162 offset:16128
	ds_read_b128 v[232:235], v162 offset:16192
	ds_write2_b32 v176, v80, v81 offset1:132
	v_add_u32_e32 v96, 0x400, v176
	ds_write2_b32 v96, v82, v83 offset0:8 offset1:140
	s_waitcnt lgkmcnt(15)
	v_mfma_f32_16x16x32_bf16 v[16:19], v[134:137], v[236:239], v[16:19]
	s_waitcnt lgkmcnt(14)
	v_mfma_f32_16x16x32_bf16 v[16:19], v[138:141], v[240:243], v[16:19]
	ds_write2_b32 v177, v84, v85 offset1:132
	v_add_u32_e32 v96, 0x400, v177
	ds_write2_b32 v96, v86, v87 offset0:8 offset1:140
	s_waitcnt lgkmcnt(15)
	v_mfma_f32_16x16x32_bf16 v[20:23], v[134:137], v[244:247], v[20:23]
	s_waitcnt lgkmcnt(14)
	v_mfma_f32_16x16x32_bf16 v[20:23], v[138:141], v[248:251], v[20:23]
	v_and_b32_e32 v98, 64, v227
	v_add_u32_e32 v98, 64, v98
	v_xor_b32_e32 v97, 1, v227
	v_cmp_lt_i32_e32 vcc, v97, v98
	s_waitcnt lgkmcnt(0)
	s_barrier
; __device__ __forceinline__ unsigned cvt_pk_bf16(float lo, float hi) { unsigned r; asm("v_cvt_pk_bf16_f32 %0, %1, %2" : "=v"(r) : "v"(lo), "v"(hi)); return r; }
; __device__ __forceinline__ void dn_seq_unit(int layer, int sample, int b, int h, unsigned char* shm) {
;     ...
;         for (int vt = 0; vt < 8; ++vt) { aS[vt] *= egl; aS[vt] = mma_tile(KDT + wid * 16 * 72, 72, VT + vt * 16 * 72, 72, 64, aS[vt], fr, fq); }
;         __syncthreads();
; #pragma unroll
;         for (int vt = 0; vt < 8; ++vt) { u32x2 o; o[0] = cvt_pk_bf16(aS[vt][0], aS[vt][1]); o[1] = cvt_pk_bf16(aS[vt][2], aS[vt][3]); *(u32x2*)(ST + (vt * 16 + fr) * 136 + wid * 16 + fq * 4) = o; }
;         { float o[16]; float ss = 0.f;
; #pragma unroll
;           for (int i = 0; i < 16; ++i) { o[i] = Of[tt * 132 + part * 16 + i]; ss += o[i] * o[i]; }
;           ss += __shfl_xor(ss, 1); ss += __shfl_xor(ss, 2); ss += __shfl_xor(ss, 4);
;           const float rs = rsqrtf(ss * (1.0f / 128) + 1e-6f);
	v_cndmask_b32_e32 v97, v227, v97, vcc
	v_lshlrev_b32_e32 v97, 2, v97
	v_mfma_f32_16x16x32_bf16 v[24:27], v[134:137], v[142:145], v[24:27]
	v_mfma_f32_16x16x32_bf16 v[24:27], v[138:141], v[146:149], v[24:27]
	v_mfma_f32_16x16x32_bf16 v[28:31], v[134:137], v[198:201], v[28:31]
	v_mfma_f32_16x16x32_bf16 v[28:31], v[138:141], v[202:205], v[28:31]
	v_mfma_f32_16x16x32_bf16 v[32:35], v[134:137], v[206:209], v[32:35]
	v_mfma_f32_16x16x32_bf16 v[32:35], v[138:141], v[232:235], v[32:35]
	v_cvt_pk_bf16_f32 v80, v4, v5
	v_cvt_pk_bf16_f32 v81, v6, v7
	ds_write_b64 v178, v[80:81] offset:62464
	v_cvt_pk_bf16_f32 v80, v8, v9
	v_cvt_pk_bf16_f32 v81, v10, v11
	ds_write_b64 v100, v[80:81] offset:62464
	v_cvt_pk_bf16_f32 v80, v12, v13
	v_cvt_pk_bf16_f32 v81, v14, v15
	ds_write_b64 v103, v[80:81] offset:62464
	v_cvt_pk_bf16_f32 v80, v16, v17
	v_cvt_pk_bf16_f32 v81, v18, v19
	ds_write_b64 v156, v[80:81] offset:62464
	v_cvt_pk_bf16_f32 v80, v20, v21
	v_cvt_pk_bf16_f32 v81, v22, v23
	ds_write_b64 v157, v[80:81] offset:62464
	v_cvt_pk_bf16_f32 v80, v24, v25
	v_cvt_pk_bf16_f32 v81, v26, v27
	ds_write_b64 v158, v[80:81] offset:62464
	v_cvt_pk_bf16_f32 v80, v28, v29
	v_cvt_pk_bf16_f32 v81, v30, v31
	ds_write_b64 v159, v[80:81] offset:62464
	v_cvt_pk_bf16_f32 v80, v32, v33
	v_cvt_pk_bf16_f32 v81, v34, v35
	ds_write_b64 v179, v[80:81] offset:62464
	ds_read_b128 v[92:95], v180
	ds_read_b128 v[88:91], v180 offset:16
	ds_read_b128 v[84:87], v180 offset:32
	ds_read_b128 v[80:83], v180 offset:48
	s_waitcnt lgkmcnt(3)
	v_mul_f32_e32 v96, v93, v93
	v_fmac_f32_e32 v96, v92, v92
	v_fmac_f32_e32 v96, v94, v94
	v_fmac_f32_e32 v96, v95, v95
	s_waitcnt lgkmcnt(2)
	v_fmac_f32_e32 v96, v88, v88
	v_fmac_f32_e32 v96, v89, v89
	v_fmac_f32_e32 v96, v90, v90
	v_fmac_f32_e32 v96, v91, v91
	s_waitcnt lgkmcnt(1)
	v_fmac_f32_e32 v96, v84, v84
	v_fmac_f32_e32 v96, v85, v85
	v_fmac_f32_e32 v96, v86, v86
	v_fmac_f32_e32 v96, v87, v87
	s_waitcnt lgkmcnt(0)
	v_fmac_f32_e32 v96, v80, v80
	v_fmac_f32_e32 v96, v81, v81
	v_fmac_f32_e32 v96, v82, v82
	v_fmac_f32_e32 v96, v83, v83
	ds_bpermute_b32 v97, v97, v96
	s_waitcnt lgkmcnt(0)
	v_add_f32_e32 v96, v96, v97
	v_xor_b32_e32 v97, 2, v227
	v_cmp_lt_i32_e32 vcc, v97, v98
	s_nop 1
	v_cndmask_b32_e32 v97, v227, v97, vcc
	v_lshlrev_b32_e32 v97, 2, v97
	ds_bpermute_b32 v97, v97, v96
	s_waitcnt lgkmcnt(0)
	v_add_f32_e32 v96, v96, v97
	v_xor_b32_e32 v97, 4, v227
	v_cmp_lt_i32_e32 vcc, v97, v98
	s_nop 1
	v_cndmask_b32_e32 v97, v227, v97, vcc
	v_lshlrev_b32_e32 v97, 2, v97
	ds_bpermute_b32 v97, v97, v96
	s_and_saveexec_b64 s[24:25], s[4:5]
	s_cbranch_execz .LBB0_776
; __device__ __forceinline__ void unpack8(u32x4 v, float* f) { f[0] = bflo(v[0]); f[1] = bfhi(v[0]); f[2] = bflo(v[1]); f[3] = bfhi(v[1]); f[4] = bflo(v[2]); f[5] = bfhi(v[2]); f[6] = bflo(v[3]); f[7] = bfhi(v[3]); }
; __device__ __forceinline__ u32x4 pack8(const float* f) { u32x4 r; r[0] = cvt_pk_bf16(f[0], f[1]); r[1] = cvt_pk_bf16(f[2], f[3]); r[2] = cvt_pk_bf16(f[4], f[5]); r[3] = cvt_pk_bf16(f[6], f[7]); return r; }
; __device__ __forceinline__ float siluf_(float x) { return x * __builtin_amdgcn_rcpf(1.0f + __expf(-x)); }
; __device__ __forceinline__ void dn_seq_unit(int layer, int sample, int b, int h, unsigned char* shm) {
;     ...
;           ss += __shfl_xor(ss, 1); ss += __shfl_xor(ss, 2); ss += __shfl_xor(ss, 4);
;           const float rs = rsqrtf(ss * (1.0f / 128) + 1e-6f);
;           if (tt < rows) { const size_t tok = tokb + n * 64 + tt; float z[16];
;               unpack8(cz[0], z); unpack8(cz[1], z + 8);
; #pragma unroll
;               for (int i = 0; i < 16; ++i) o[i] = o[i] * rs * dnn[part * 16 + i] * siluf_(z[i]);
;               bf16_t* d = BR1 + tok * 1024 + h * 128 + part * 16; *(u32x4*)d = pack8(o); *(u32x4*)(d + 8) = pack8(o + 8); } }
	s_waitcnt lgkmcnt(0)
	v_add_f32_e32 v96, v96, v97
	v_fmamk_f32 v96, v96, 0x3c000000, v219
	v_cmp_gt_f32_e32 vcc, s91, v96
	v_mul_f32_e32 v97, 0x4b800000, v96
	v_lshlrev_b32_e32 v202, 16, v76
	v_cndmask_b32_e32 v96, v96, v97, vcc
	v_rsq_f32_e32 v96, v96
	v_lshlrev_b32_e32 v148, 16, v72
	v_and_b32_e32 v146, 0xffff0000, v72
	v_add_u32_e32 v72, 0, v164
	v_mul_f32_e32 v97, 0x45800000, v96
	v_cndmask_b32_e32 v135, v96, v97, vcc
	v_mul_f32_e32 v231, v92, v135
	v_mul_f32_e32 v92, 0xbfb8aa3b, v202
	v_exp_f32_e32 v92, v92
	v_add_u32_e32 v72, 0x24800, v72
	v_and_b32_e32 v204, 0xffff0000, v76
	v_lshlrev_b32_e32 v206, 16, v77
	v_add_f32_e32 v92, 1.0, v92
	v_rcp_f32_e32 v230, v92
	v_and_b32_e32 v208, 0xffff0000, v77
	v_lshlrev_b32_e32 v210, 16, v78
	v_and_b32_e32 v228, 0xffff0000, v78
	v_lshlrev_b32_e32 v152, 16, v79
	v_and_b32_e32 v150, 0xffff0000, v79
	v_lshlrev_b32_e32 v144, 16, v73
	v_and_b32_e32 v142, 0xffff0000, v73
	v_lshlrev_b32_e32 v140, 16, v74
	v_and_b32_e32 v138, 0xffff0000, v74
	v_lshlrev_b32_e32 v136, 16, v75
	v_and_b32_e32 v134, 0xffff0000, v75
	ds_read_b128 v[198:201], v72
	ds_read_b128 v[96:99], v72 offset:16
	ds_read_b128 v[76:79], v72 offset:32
	ds_read_b128 v[72:75], v72 offset:48
	v_mul_f32_e32 v95, v95, v135
	s_waitcnt lgkmcnt(3)
	v_mov_b32_e32 v203, v198
	v_pk_mul_f32 v[202:203], v[230:231], v[202:203]
	v_mov_b32_e32 v205, v199
	v_mul_f32_e32 v92, v202, v203
	v_mul_f32_e32 v203, v93, v135
	v_mul_f32_e32 v93, 0xbfb8aa3b, v204
	v_exp_f32_e32 v93, v93
	v_mov_b32_e32 v207, v200
	v_mov_b32_e32 v209, v201
	s_waitcnt lgkmcnt(2)
	v_mov_b32_e32 v211, v96
	v_add_f32_e32 v93, 1.0, v93
	v_rcp_f32_e32 v202, v93
	v_mul_f32_e32 v89, v89, v135
	v_mov_b32_e32 v229, v97
	v_mov_b32_e32 v153, v98
	v_pk_mul_f32 v[198:199], v[202:203], v[204:205]
	v_mov_b32_e32 v151, v99
	v_mul_f32_e32 v93, v198, v199
	v_mul_f32_e32 v199, v94, v135
	v_mul_f32_e32 v94, 0xbfb8aa3b, v206
	v_exp_f32_e32 v94, v94
	s_waitcnt lgkmcnt(1)
	v_mov_b32_e32 v149, v76
	v_mul_f32_e32 v76, 0xbfb8aa3b, v146
	v_exp_f32_e32 v76, v76
	v_add_f32_e32 v94, 1.0, v94
	v_rcp_f32_e32 v198, v94
	v_mul_f32_e32 v94, 0xbfb8aa3b, v208
	v_exp_f32_e32 v94, v94
	v_add_f32_e32 v76, 1.0, v76
	v_pk_mul_f32 v[198:199], v[198:199], v[206:207]
	v_mul_f32_e32 v85, v85, v135
	v_add_f32_e32 v94, 1.0, v94
	v_rcp_f32_e32 v94, v94
	v_mul_f32_e32 v198, v198, v199
	v_mov_b32_e32 v147, v77
	v_mov_b32_e32 v145, v78
	v_pk_mul_f32 v[94:95], v[94:95], v[208:209]
	v_mov_b32_e32 v143, v79
	v_mul_f32_e32 v199, v94, v95
	v_mul_f32_e32 v95, v88, v135
	v_mul_f32_e32 v88, 0xbfb8aa3b, v210
	v_exp_f32_e32 v88, v88
	s_waitcnt lgkmcnt(0)
	v_mov_b32_e32 v141, v72
	v_mul_f32_e32 v72, 0xbfb8aa3b, v138
	v_exp_f32_e32 v72, v72
	v_add_f32_e32 v88, 1.0, v88
	v_rcp_f32_e32 v94, v88
	v_mul_f32_e32 v88, 0xbfb8aa3b, v228
	v_exp_f32_e32 v88, v88
	v_add_f32_e32 v72, 1.0, v72
	v_pk_mul_f32 v[94:95], v[94:95], v[210:211]
	v_mov_b32_e32 v139, v73
	v_add_f32_e32 v88, 1.0, v88
	v_rcp_f32_e32 v88, v88
	v_mul_f32_e32 v94, v94, v95
	v_mov_b32_e32 v137, v74
	s_mov_b32 s23, s34
	v_pk_mul_f32 v[88:89], v[88:89], v[228:229]
	s_nop 0
	v_mul_f32_e32 v95, v88, v89
	v_mul_f32_e32 v88, 0xbfb8aa3b, v152
	v_exp_f32_e32 v88, v88
	v_mul_f32_e32 v89, v90, v135
	v_cvt_pk_bf16_f32 v74, v94, v95
	v_add_f32_e32 v88, 1.0, v88
	v_rcp_f32_e32 v88, v88
	s_nop 0
	v_pk_mul_f32 v[88:89], v[88:89], v[152:153]
	s_nop 0
	v_mul_f32_e32 v90, v88, v89
	v_mul_f32_e32 v88, 0xbfb8aa3b, v150
	v_exp_f32_e32 v88, v88
	v_mul_f32_e32 v89, v91, v135
	v_add_f32_e32 v88, 1.0, v88
	v_rcp_f32_e32 v88, v88
	s_nop 0
	v_pk_mul_f32 v[88:89], v[88:89], v[150:151]
	s_nop 0
	v_mul_f32_e32 v91, v88, v89
	v_mul_f32_e32 v89, v84, v135
	v_mul_f32_e32 v84, 0xbfb8aa3b, v148
	v_exp_f32_e32 v84, v84
	s_nop 0
	v_add_f32_e32 v84, 1.0, v84
	v_rcp_f32_e32 v88, v84
	v_rcp_f32_e32 v84, v76
	v_pk_mul_f32 v[88:89], v[88:89], v[148:149]
	v_pk_mul_f32 v[76:77], v[84:85], v[146:147]
	v_mul_f32_e32 v88, v88, v89
	v_mul_f32_e32 v84, v76, v77
	v_mul_f32_e32 v76, 0xbfb8aa3b, v144
	v_exp_f32_e32 v76, v76
	v_mul_f32_e32 v77, v86, v135
	v_add_f32_e32 v76, 1.0, v76
	v_rcp_f32_e32 v76, v76
	s_nop 0
	v_pk_mul_f32 v[76:77], v[76:77], v[144:145]
	s_nop 0
	v_mul_f32_e32 v78, v76, v77
	v_mul_f32_e32 v76, 0xbfb8aa3b, v142
	v_exp_f32_e32 v76, v76
	v_mul_f32_e32 v77, v87, v135
	v_add_f32_e32 v76, 1.0, v76
	v_rcp_f32_e32 v76, v76
	s_nop 0
	v_pk_mul_f32 v[76:77], v[76:77], v[142:143]
	s_nop 0
	v_mul_f32_e32 v79, v76, v77
	v_mul_f32_e32 v76, 0xbfb8aa3b, v140
	v_exp_f32_e32 v76, v76
	v_mul_f32_e32 v77, v80, v135
	v_add_f32_e32 v76, 1.0, v76
	v_rcp_f32_e32 v76, v76
	s_nop 0
	v_pk_mul_f32 v[76:77], v[76:77], v[140:141]
	s_nop 0
	v_mul_f32_e32 v80, v76, v77
	v_rcp_f32_e32 v76, v72
	v_mul_f32_e32 v77, v81, v135
	v_pk_mul_f32 v[72:73], v[76:77], v[138:139]
	s_nop 0
	v_mul_f32_e32 v81, v72, v73
	v_mul_f32_e32 v72, 0xbfb8aa3b, v136
	v_exp_f32_e32 v72, v72
	v_mul_f32_e32 v73, v82, v135
	v_add_f32_e32 v72, 1.0, v72
	v_rcp_f32_e32 v72, v72
	s_nop 0
	v_pk_mul_f32 v[72:73], v[72:73], v[136:137]
	s_nop 0
	v_mul_f32_e32 v82, v72, v73
	v_mul_f32_e32 v72, 0xbfb8aa3b, v134
	v_exp_f32_e32 v72, v72
	v_mul_f32_e32 v73, v83, v135
	v_mov_b32_e32 v135, v75
	v_cvt_pk_bf16_f32 v75, v90, v91
	v_add_f32_e32 v72, 1.0, v72
	v_rcp_f32_e32 v72, v72
	s_nop 0
	v_pk_mul_f32 v[72:73], v[72:73], v[134:135]
	s_nop 0
	v_mul_f32_e32 v83, v72, v73
	v_lshl_add_u64 v[72:73], v[124:125], 0, s[22:23]
	v_lshlrev_b64 v[72:73], 11, v[72:73]
	v_lshl_add_u64 v[76:77], v[2:3], 0, v[72:73]
	v_cvt_pk_bf16_f32 v72, v92, v93
	v_cvt_pk_bf16_f32 v73, v198, v199
	global_store_dwordx4 v[76:77], v[72:75], off
	s_nop 1
	v_cvt_pk_bf16_f32 v72, v88, v84
	v_cvt_pk_bf16_f32 v73, v78, v79
	v_cvt_pk_bf16_f32 v74, v80, v81
	v_cvt_pk_bf16_f32 v75, v82, v83
	global_store_dwordx4 v[76:77], v[72:75], off offset:16
